# nsa selected branch: the stage's selection word is read once, before the DMA issue code, instead of per tile
# speedup vs baseline: 1.0020x; 1.0020x over previous
; template <class F>
; DI void kv_pipeline(int jlo, int jhi, const u16* kb, int ldk, const u16* vb, int ldv, char* smem, int tid, F&& body) {
;     ...
;   __syncthreads();
;   KV_ISSUE(jlo, 0);
;   if (jlo + 1 <= jhi) KV_ISSUE(jlo + 1, 1);
;   asm volatile("s_waitcnt vmcnt(0)" ::: "memory");
;   __syncthreads();
;   int buf = 0;
;   for (int j = jlo; j <= jhi; j += 2) {
;     if (j + 2 <= jhi) KV_ISSUE(j + 2, (buf ^ 1) * 2);
;     if (j + 3 <= jhi) KV_ISSUE(j + 3, (buf ^ 1) * 2 + 1);
; DI void nsa_item(const Params& p, int b, int g, int qb, char* smem, int tid) {
;     ...
;       const bool sb = (sel[qi * 4 + (j >> 5)] >> (j & 31)) & 1u;
.LBB0_809:
	s_lshr_b32 s38, s56, 3
	s_and_b32 s38, s38, 0x1ffffffc
	v_add_u32_e32 v172, s38, v171
	ds_read_b32 v172, v172
	s_add_i32 s0, s56, 2
	s_cmp_gt_u32 s0, s2
	s_cselect_b64 s[50:51], -1, 0
	s_and_b64 vcc, exec, s[50:51]
	s_cbranch_vccnz .LBB0_811
	s_lshl_b64 s[38:39], s[0:1], 15
	s_add_u32 s38, s42, s38
	s_addc_u32 s39, s43, s39
	s_lshl_b64 s[46:47], s[0:1], 7
	s_add_u32 s46, s44, s46
	s_addc_u32 s47, s45, s47
	s_lshl_b32 s48, s55, 16
	s_xor_b32 s48, s48, 0x10000
	s_add_i32 s48, s54, s48
	s_add_i32 s49, s48, 0x4000
	v_lshl_add_u64 v[0:1], s[38:39], 0, v[16:17]
	s_mov_b32 m0, s48
	s_nop 0
	global_load_lds_dwordx4 v[0:1], off
	v_lshl_add_u64 v[0:1], s[46:47], 0, v[162:163]
	s_mov_b32 m0, s49
	s_nop 0
	global_load_lds_dwordx4 v[0:1], off
	v_lshl_add_u64 v[0:1], s[38:39], 0, v[164:165]
	s_add_i32 m0, s48, 0x2000
	s_nop 0
	global_load_lds_dwordx4 v[0:1], off
	v_lshl_add_u64 v[0:1], s[46:47], 0, v[166:167]
	s_add_i32 m0, s48, 0x6000
	s_nop 0
	global_load_lds_dwordx4 v[0:1], off

; template <class F>
; DI void kv_pipeline(int jlo, int jhi, const u16* kb, int ldk, const u16* vb, int ldv, char* smem, int tid, F&& body) {
;     ...
; #pragma unroll 1
;     for (int t = 0; t < 2; ++t) {
;       if (j + t > jhi) break;
;       const char* tb = (const char*)(smem + buf * 65536 + t * 32768);
;       body(j + t, tb, tb + 16384);
.LBB0_815:
	s_lshr_b32 s38, s56, 3
	s_and_b32 s38, s38, 0x1ffffffc
	s_add_i32 s57, s39, 0
	s_mov_b32 s48, 0
	s_mov_b64 s[46:47], -1
	s_branch .LBB0_817

; #define SB0 __builtin_amdgcn_sched_barrier(0)
; DI void nsa_S(f32x4 (&s)[4], const char* Kb, const char* Vb, const bf16x8 (&qf)[4], bf16x8 (&v0)[4], int lr, int quad) {
;   bf16x8 k0[4], k1[4], k2[4], k3[4];
;   ldk4(k0, Kb, 0, lr, quad); SB0;
;   ldk4(k1, Kb, 1, lr, quad); s[0] = mma4(k0, qf); SB0;
;   ldk4(k2, Kb, 2, lr, quad); s[1] = mma4(k1, qf); SB0;
;   ldk4(k3, Kb, 3, lr, quad); s[2] = mma4(k2, qf); SB0;
;   ldv4(v0, Vb, 0, lr, quad); s[3] = mma4(k3, qf); SB0;
; }
; DI void nsa_item(const Params& p, int b, int g, int qb, char* smem, int tid) {
;     ...
;       const bool sb = (sel[qi * 4 + (j >> 5)] >> (j & 31)) & 1u;
;       if (!__any(sb)) return;
;       f32x4 s[4];
;       bf16x8 va[4];
;       nsa_S(s, Kb, Vb, qf, va, lr, quad);
;       auto mf = [&](int kt, int i) __attribute__((always_inline)) { return j * 64 + kt * 16 + quad * 4 + i > qp; };
;       if (j == cur) flash_update<true>(s, SCL, mx2, l2, o, mf, sb);
;       else flash_update<false>(s, SCL, mx2, l2, o, mf, sb);
.LBB0_817:
	s_or_b32 s59, s48, s56
	s_cmp_gt_u32 s59, s2
	s_cbranch_scc1 .LBB0_816
	s_and_b32 s38, s59, 31
	s_waitcnt lgkmcnt(0)
	v_mov_b32_e32 v0, v172
	v_lshrrev_b32_e32 v1, s59, v0
	v_bfe_u32 v0, v0, s38, 1
	v_and_b32_e32 v1, 1, v1
	v_cmp_ne_u32_e32 vcc, 0, v0
	v_cmp_eq_u32_e64 s[38:39], 1, v1
	s_cbranch_vccz .LBB0_829
	s_lshl_b32 s48, s48, 15
	s_add_i32 s58, s57, s48
	v_add_u32_e32 v8, s58, v234
	v_add_u32_e32 v122, v8, v235
	v_add_u32_e32 v124, v8, v237
	v_add_u32_e32 v123, v8, v236
	ds_read_b128 v[0:3], v122
	ds_read_b128 v[4:7], v123
	v_add_u32_e32 v125, v8, v238
	ds_read_b128 v[8:11], v124
	ds_read_b128 v[12:15], v125
	ds_read_b128 v[98:101], v122 offset:4096
	ds_read_b128 v[102:105], v123 offset:4096
	ds_read_b128 v[106:109], v124 offset:4096
	ds_read_b128 v[110:113], v125 offset:4096
	s_setprio 1
	s_waitcnt lgkmcnt(7)
	v_mfma_f32_16x16x32_bf16 v[0:3], v[0:3], v[18:21], 0
	s_waitcnt lgkmcnt(6)
	v_mfma_f32_16x16x32_bf16 v[0:3], v[4:7], v[22:25], v[0:3]
	s_waitcnt lgkmcnt(5)
	v_mfma_f32_16x16x32_bf16 v[0:3], v[8:11], v[26:29], v[0:3]
	s_waitcnt lgkmcnt(4)
	v_mfma_f32_16x16x32_bf16 v[114:117], v[12:15], v[30:33], v[0:3]
	s_setprio 0
	s_nop 5
	ds_read_b128 v[0:3], v122 offset:8192
	ds_read_b128 v[4:7], v123 offset:8192
	ds_read_b128 v[8:11], v124 offset:8192
	ds_read_b128 v[12:15], v125 offset:8192
	s_setprio 1
	s_waitcnt lgkmcnt(7)
	v_mfma_f32_16x16x32_bf16 v[98:101], v[98:101], v[18:21], 0
	s_waitcnt lgkmcnt(6)
	v_mfma_f32_16x16x32_bf16 v[98:101], v[102:105], v[22:25], v[98:101]
	s_waitcnt lgkmcnt(5)
	v_mfma_f32_16x16x32_bf16 v[98:101], v[106:109], v[26:29], v[98:101]
	s_waitcnt lgkmcnt(4)
	v_mfma_f32_16x16x32_bf16 v[118:121], v[110:113], v[30:33], v[98:101]
	s_setprio 0
	ds_read_b128 v[126:129], v122 offset:12288
	ds_read_b128 v[130:133], v123 offset:12288
	ds_read_b128 v[134:137], v124 offset:12288
	ds_read_b128 v[138:141], v125 offset:12288
	s_setprio 1
	s_waitcnt lgkmcnt(7)
	v_mfma_f32_16x16x32_bf16 v[0:3], v[0:3], v[18:21], 0
	s_waitcnt lgkmcnt(6)
	v_mfma_f32_16x16x32_bf16 v[0:3], v[4:7], v[22:25], v[0:3]
	s_waitcnt lgkmcnt(5)
	v_mfma_f32_16x16x32_bf16 v[0:3], v[8:11], v[26:29], v[0:3]
	s_waitcnt lgkmcnt(4)
	v_mfma_f32_16x16x32_bf16 v[122:125], v[12:15], v[30:33], v[0:3]
	s_setprio 0
	s_nop 5
	v_add_u32_e32 v0, s58, v242
	v_add_u32_e32 v174, v0, v241
	ds_read_b128 v[98:101], v174 offset:16384
	ds_read_b128 v[102:105], v174 offset:18432
	ds_read_b128 v[106:109], v174 offset:20480
	ds_read_b128 v[110:113], v174 offset:22528
	s_setprio 1
	s_waitcnt lgkmcnt(7)
	v_mfma_f32_16x16x32_bf16 v[0:3], v[126:129], v[18:21], 0
	s_waitcnt lgkmcnt(6)
	v_mfma_f32_16x16x32_bf16 v[0:3], v[130:133], v[22:25], v[0:3]
	s_waitcnt lgkmcnt(5)
	v_mfma_f32_16x16x32_bf16 v[0:3], v[134:137], v[26:29], v[0:3]
	s_waitcnt lgkmcnt(4)
	v_mfma_f32_16x16x32_bf16 v[126:129], v[138:141], v[30:33], v[0:3]
	s_setprio 0
	s_mov_b64 s[48:49], -1
	s_cmp_lg_u32 s59, s2
	v_add_f32_e32 v176, 0x427af232, v173
	s_cbranch_scc0 .LBB0_823
	s_nop 1
	v_max3_f32 v0, v114, s41, v115
	v_max3_f32 v0, v0, v116, v117
	v_max3_f32 v0, v0, v118, v119
	v_max3_f32 v0, v0, v120, v121
	v_max3_f32 v0, v0, v122, v123
	v_max3_f32 v0, v0, v124, v125
	v_max3_f32 v0, v0, v126, v127
	v_max3_f32 v0, v0, v128, v129
	v_mov_b32_e32 v1, v0
	s_nop 1
	v_permlane16_swap_b32_e32 v0, v1
	v_max_f32_e32 v1, v1, v1
	v_max_f32_e32 v0, v0, v0
	v_max_f32_e32 v0, v0, v1
	v_mov_b32_e32 v1, v0
	s_nop 1
	v_permlane32_swap_b32_e32 v0, v1
	v_max_f32_e32 v1, v1, v1
	v_max_f32_e32 v0, v0, v0
	v_max_f32_e32 v0, v0, v1
	v_cndmask_b32_e64 v0, v231, v0, s[38:39]
	v_mov_b64_e32 v[160:161], v[68:69]
	v_mov_b64_e32 v[156:157], v[72:73]
	v_mov_b64_e32 v[152:153], v[76:77]
	v_mov_b64_e32 v[148:149], v[80:81]
	v_mov_b64_e32 v[144:145], v[84:85]
	v_mov_b64_e32 v[140:141], v[88:89]
	v_mov_b64_e32 v[136:137], v[92:93]
	v_mov_b64_e32 v[132:133], v[96:97]
	v_cmp_gt_f32_e32 vcc, v0, v176
	v_mov_b64_e32 v[158:159], v[66:67]
	v_mov_b64_e32 v[154:155], v[70:71]
	v_mov_b64_e32 v[150:151], v[74:75]
	v_mov_b64_e32 v[146:147], v[78:79]
	v_mov_b64_e32 v[142:143], v[82:83]
	v_mov_b64_e32 v[138:139], v[86:87]
	v_mov_b64_e32 v[134:135], v[90:91]
	v_mov_b64_e32 v[130:131], v[94:95]
	v_mov_b32_e32 v177, v170
	v_mov_b32_e32 v175, v173
	s_cbranch_vccz .LBB0_822
	v_max_f32_e32 v0, v0, v0
	v_max_f32_e32 v1, v173, v173
	v_max_f32_e32 v175, v1, v0
	v_sub_f32_e32 v0, v173, v175
	v_mul_f32_e32 v0, 0x3e0293ee, v0
	v_exp_f32_e32 v0, v0
	s_nop 0
	v_mul_f32_e32 v177, v170, v0
	v_pk_mul_f32 v[132:133], v[96:97], v[0:1] op_sel_hi:[1,0]
	v_pk_mul_f32 v[130:131], v[94:95], v[0:1] op_sel_hi:[1,0]
	v_pk_mul_f32 v[136:137], v[92:93], v[0:1] op_sel_hi:[1,0]
	v_pk_mul_f32 v[134:135], v[90:91], v[0:1] op_sel_hi:[1,0]
	v_pk_mul_f32 v[140:141], v[88:89], v[0:1] op_sel_hi:[1,0]
	v_pk_mul_f32 v[138:139], v[86:87], v[0:1] op_sel_hi:[1,0]
	v_pk_mul_f32 v[144:145], v[84:85], v[0:1] op_sel_hi:[1,0]
	v_pk_mul_f32 v[142:143], v[82:83], v[0:1] op_sel_hi:[1,0]
	v_pk_mul_f32 v[148:149], v[80:81], v[0:1] op_sel_hi:[1,0]
	v_pk_mul_f32 v[146:147], v[78:79], v[0:1] op_sel_hi:[1,0]
	v_pk_mul_f32 v[152:153], v[76:77], v[0:1] op_sel_hi:[1,0]
	v_pk_mul_f32 v[150:151], v[74:75], v[0:1] op_sel_hi:[1,0]
	v_pk_mul_f32 v[156:157], v[72:73], v[0:1] op_sel_hi:[1,0]
	v_pk_mul_f32 v[154:155], v[70:71], v[0:1] op_sel_hi:[1,0]
	v_pk_mul_f32 v[160:161], v[68:69], v[0:1] op_sel_hi:[1,0]
	v_pk_mul_f32 v[158:159], v[66:67], v[0:1] op_sel_hi:[1,0]
